# v50: v49 + NA units re-indexed by XCD token ownership so the NA->out-proj boundary is an XCD-local barrier (guard ok and grid 256)
# baseline (speedup 1.0000x reference)
.LBB0_274:
	v_mov_b32_e32 v0, v234
	s_and_b32 s39, s47, 1
	s_lshl_b32 s39, s39, 6
	s_bfe_u32 s2, s47, 0x1000a
	s_lshl_b32 s2, s2, 5
	s_or_b32 s39, s39, s2
	s_bfe_u32 s2, s47, 0x50003
	s_or_b32 s39, s39, s2
	v_readfirstlane_b32 s2, v0
	s_bfe_u32 s37, s47, 0x20001
	s_bfe_u32 s36, s2, 0x20006
	s_ashr_i32 s2, s2, 3
	v_mov_b32_e32 v1, s2
	s_lshl_b32 s17, s37, 13
	s_lshl_b32 s2, s39, 6
	v_bfi_b32 v4, s73, v1, v0
	s_or_b32 s2, s2, s17
	s_bfe_u32 s34, s47, 0x20008
	s_waitcnt vmcnt(19)
	v_add_u32_e32 v144, s2, v4
	v_ashrrev_i32_e32 v145, 31, v144
	s_lshl_b32 s38, s34, 8
	s_lshl_b32 s2, s36, 6
	v_lshlrev_b64 v[2:3], 12, v[144:145]
	s_or_b32 s2, s2, s38
	v_bfe_u32 v5, v0, 5, 1
	v_lshl_add_u64 v[2:3], s[18:19], 0, v[2:3]
	s_lshl_b32 s70, s2, 1
	v_lshl_add_u64 v[2:3], v[2:3], 0, s[70:71]
	v_lshlrev_b32_e32 v146, 4, v5
	v_mov_b32_e32 v147, v201
	v_lshl_add_u64 v[2:3], v[2:3], 0, v[146:147]
	global_load_dwordx4 v[96:99], v[2:3], off
	global_load_dwordx4 v[100:103], v[2:3], off offset:32
	global_load_dwordx4 v[104:107], v[2:3], off offset:64
	global_load_dwordx4 v[108:111], v[2:3], off offset:96
	s_movk_i32 s2, 0x744
	s_bfe_u32 s16, s22, 0x20008
	v_cmp_gt_i32_e32 vcc, s2, v0
	s_and_saveexec_b64 s[2:3], vcc
	s_cbranch_execz .LBB0_282
	v_max_i32_e32 v1, 0x544, v0
	v_sub_u32_e32 v1, v1, v0
	v_add_u32_e32 v1, 0x1ff, v1
	s_movk_i32 s4, 0x1ff
	v_cmp_lt_u32_e32 vcc, s4, v1
	s_mov_b64 s[6:7], -1
	v_mov_b32_e32 v2, v0
	s_and_saveexec_b64 s[4:5], vcc
	s_cbranch_execz .LBB0_279
	s_mulk_i32 s34, 0x1d10
	v_readlane_b32 s0, v255, 32
	v_lshrrev_b32_e32 v1, 9, v1
	s_add_u32 s6, s0, s34
	v_readlane_b32 s0, v255, 33
	v_add_u32_e32 v6, 1, v1
	s_addc_u32 s7, s0, 0
	v_and_b32_e32 v7, 0xfffffe, v6
	v_add_u32_e32 v1, 0x200, v0
	v_readlane_b32 s0, v255, 14
	s_mov_b64 s[34:35], 0
	v_mov_b32_e32 v9, v7
	v_lshl_add_u32 v8, v0, 2, s0
	v_mov_b64_e32 v[2:3], v[0:1]

.LBB0_282:
	s_or_b64 exec, exec, s[2:3]
	s_max_u32 s99, s39, 4
	s_min_u32 s99, s99, 0x7c
	s_sub_u32 s99, 4, s99
	s_and_b32 s99, s99, 7
	s_mul_i32 s98, s99, 0x7c
	v_med3_u32 v1, s39, 4, v241
	v_lshlrev_b32_e32 v2, 4, v0
	v_lshlrev_b32_e32 v1, 6, v1
	v_and_b32_e32 v200, 0x70, v2
	v_add_u32_e32 v2, 0xffffff00, v1
	v_ashrrev_i32_e32 v10, 3, v0
	v_add_u32_e32 v1, s17, v2
	v_add_u32_e32 v6, v1, v10
	v_ashrrev_i32_e32 v7, 31, v6
	v_lshlrev_b64 v[6:7], 12, v[6:7]
	v_lshl_add_u64 v[6:7], s[18:19], 0, v[6:7]
	s_lshl_b32 s2, s38, 1
	s_mov_b32 s3, s71
	s_lshl_b32 s6, s37, 10
	v_lshl_add_u64 v[6:7], v[6:7], 0, s[2:3]
	s_lshl_b32 s13, s99, 18
	v_add_co_u32_e32 v6, vcc, s13, v6
	v_addc_co_u32_e32 v7, vcc, 0, v7, vcc
	s_or_b32 s2, s6, s38
	v_add_u32_e32 v8, s2, v10
	v_ashrrev_i32_e32 v9, 31, v8
	v_lshlrev_b64 v[8:9], 14, v[8:9]
	v_lshl_add_u64 v[8:9], s[68:69], 0, v[8:9]
	v_mov_b32_e32 v3, v201
	v_lshl_add_u64 v[2:3], v[2:3], 1, v[8:9]
	v_lshl_add_u64 v[2:3], v[2:3], 0, v[200:201]
	s_lshl_b32 s13, s99, 7
	v_add_co_u32_e32 v2, vcc, s13, v2
	v_addc_co_u32_e32 v3, vcc, 0, v3, vcc
	v_add_co_u32_e32 v8, vcc, s72, v2
	s_mov_b32 s2, 0x200000
	s_nop 0
	v_addc_co_u32_e32 v9, vcc, 0, v3, vcc
	global_load_dwordx4 v[112:115], v[2:3], off
	global_load_dwordx4 v[116:119], v[8:9], off
	v_add_co_u32_e32 v8, vcc, s2, v2
	s_mov_b32 s2, 0x300000
	s_nop 0
	v_addc_co_u32_e32 v9, vcc, 0, v3, vcc
	v_add_co_u32_e32 v2, vcc, s2, v2
	v_lshl_add_u64 v[6:7], v[6:7], 0, v[200:201]
	s_nop 0
	v_addc_co_u32_e32 v3, vcc, 0, v3, vcc
	global_load_dwordx4 v[132:135], v[8:9], off
	global_load_dwordx4 v[140:143], v[2:3], off
	global_load_dwordx4 v[120:123], v[6:7], off offset:2048
	global_load_dwordx4 v[124:127], v[6:7], off offset:2176
	global_load_dwordx4 v[128:131], v[6:7], off offset:2304
	global_load_dwordx4 v[136:139], v[6:7], off offset:2432
	v_and_b32_e32 v3, 31, v0
	v_and_b32_e32 v2, 19, v0
	v_lshrrev_b32_e32 v0, 1, v0
	v_mul_lo_u32 v6, v10, s24
	v_lshlrev_b32_e32 v7, 1, v3
	s_waitcnt vmcnt(30)
	v_lshlrev_b32_e32 v148, 3, v5
	v_med3_i32 v5, v4, 8, 56
	v_and_b32_e32 v0, 4, v0
	v_add3_u32 v147, v6, v200, 0
	v_and_b32_e32 v6, 8, v7
	v_sub_u32_e32 v5, v148, v5
	v_or3_b32 v2, v2, v6, v0
	v_mul_u32_u24_e32 v149, 0x90, v2
	v_add_u32_e32 v2, 10, v5
	v_cmp_gt_u32_e64 s[52:53], 16, v2
	v_add_u32_e32 v2, 11, v5
	v_cmp_gt_u32_e64 s[54:55], 16, v2
	v_add_u32_e32 v2, 12, v5
	v_cmp_gt_u32_e64 s[56:57], 16, v2
	v_add_u32_e32 v2, 13, v5
	v_cmp_gt_u32_e64 s[58:59], 16, v2
	v_add_u32_e32 v2, 14, v5
	v_cmp_gt_u32_e64 s[60:61], 16, v2
	v_add_u32_e32 v2, 15, v5
	v_cmp_gt_u32_e64 s[62:63], 16, v2
	v_add_u32_e32 v2, 25, v5
	v_add_u32_e32 v6, 41, v5
	v_cmp_gt_u32_e64 s[66:67], 16, v2
	v_add_u32_e32 v2, 26, v5
	v_cmp_gt_u32_e64 s[82:83], 16, v6
	v_add_u32_e32 v6, 42, v5
	s_mov_b64 s[14:15], s[68:69]
	v_cmp_gt_u32_e64 s[68:69], 16, v2
	v_add_u32_e32 v2, 27, v5
	v_cmp_gt_u32_e64 s[84:85], 16, v6
	v_add_u32_e32 v6, 43, v5
	s_mov_b64 s[0:1], s[70:71]
	s_lshr_b32 s2, s47, 2
	v_cmp_gt_u32_e64 s[70:71], 16, v2
	v_add_u32_e32 v2, 28, v5
	v_cmp_gt_u32_e64 s[86:87], 16, v6
	v_add_u32_e32 v6, 44, v5
	s_and_b32 s35, s47, 1
	s_lshl_b32 s35, s35, 6
	s_bfe_u32 s2, s47, 0x1000a
	s_lshl_b32 s2, s2, 5
	s_or_b32 s35, s35, s2
	s_bfe_u32 s2, s47, 0x50003
	s_or_b32 s35, s35, s2
	v_cmp_gt_u32_e64 s[72:73], 16, v2
	v_add_u32_e32 v2, 29, v5
	v_cmp_gt_u32_e64 s[88:89], 16, v6
	v_add_u32_e32 v6, 45, v5
	v_sub_u32_e32 v4, v148, v4
	v_med3_u32 v8, s35, 4, v241
	v_cmp_gt_u32_e64 s[74:75], 16, v2
	v_add_u32_e32 v2, 30, v5
	v_cmp_gt_u32_e64 s[90:91], 16, v6
	v_add_u32_e32 v6, 46, v5
	s_mul_i32 s3, s36, 0x4800
	v_add_u32_e32 v7, 8, v5
	v_add_u32_e32 v4, 15, v4
	v_add_u32_e32 v9, 9, v5
	s_movk_i32 s2, 0x7c
	v_lshlrev_b32_e32 v12, 7, v8
	s_movk_i32 s4, 0xffef
	v_cmp_gt_u32_e64 s[76:77], 16, v2
	v_add_u32_e32 v2, 31, v5
	v_cmp_gt_u32_e64 s[92:93], 16, v6
	v_add_u32_e32 v6, 47, v5
	s_add_i32 s37, s3, 0
	v_mul_lo_u32 v11, v8, s2
	v_cmp_gt_u32_e64 s[2:3], 16, v7
	v_add_u32_e32 v0, 0xfffffe00, v12
	v_cmp_gt_u32_e64 s[48:49], 16, v9
	v_cmp_lt_u32_e64 s[64:65], s4, v7
	v_cmp_gt_u32_e64 s[78:79], 16, v2
	v_and_b32_e32 v2, -16, v7
	s_movk_i32 s4, 0xffe0
	v_cmp_gt_u32_e64 s[94:95], 16, v6
	v_med3_i32 v6, v4, 0, 30
	v_max_i32_e32 v7, -1, v4
	v_max_i32_e32 v9, -2, v4
	v_max_i32_e32 v12, -3, v4
	v_max_i32_e32 v13, -4, v4
	v_max_i32_e32 v14, -5, v4
	v_max_i32_e32 v15, -6, v4
	v_max_i32_e32 v16, -7, v4
	v_max_i32_e32 v17, -16, v4
	v_max_i32_e32 v18, 0xffffffef, v4
	v_max_i32_e32 v19, 0xffffffee, v4
	v_max_i32_e32 v20, 0xffffffed, v4
	v_max_i32_e32 v21, 0xffffffec, v4
	v_max_i32_e32 v22, 0xffffffeb, v4
	v_max_i32_e32 v23, 0xffffffea, v4
	v_max_i32_e32 v24, 0xffffffe9, v4
	v_max_i32_e32 v25, 0xffffffe0, v4
	v_max_i32_e32 v26, 0xffffffdf, v4
	v_max_i32_e32 v27, 0xffffffde, v4
	v_max_i32_e32 v28, 0xffffffdd, v4
	v_max_i32_e32 v29, 0xffffffdc, v4
	v_max_i32_e32 v30, 0xffffffdb, v4
	v_max_i32_e32 v31, 0xffffffda, v4
	v_max_i32_e32 v32, 0xffffffd9, v4
	v_max_i32_e32 v33, 0xffffffd0, v4
	v_max_i32_e32 v34, 0xffffffcf, v4
	v_max_i32_e32 v35, 0xffffffce, v4
	v_max_i32_e32 v36, 0xffffffcd, v4
	v_max_i32_e32 v37, 0xffffffcc, v4
	v_max_i32_e32 v38, 0xffffffcb, v4
	v_max_i32_e32 v39, 0xffffffca, v4
	v_max_i32_e32 v4, 0xffffffc9, v4
	v_cmp_eq_u32_e64 s[80:81], s4, v2
	s_movk_i32 s4, 0xffd0
	v_add_u32_e32 v4, 55, v4
	s_mulk_i32 s36, 0x744
	v_cmp_eq_u32_e64 s[96:97], s4, v2
	v_add_u32_e32 v2, 57, v5
	v_add_u32_e32 v7, 1, v7
	v_add_u32_e32 v9, 2, v9
	v_add_u32_e32 v12, 3, v12
	v_add_u32_e32 v13, 4, v13
	v_add_u32_e32 v14, 5, v14
	v_add_u32_e32 v15, 6, v15
	v_add_u32_e32 v16, 7, v16
	v_add_u32_e32 v17, 16, v17
	v_add_u32_e32 v18, 17, v18
	v_add_u32_e32 v19, 18, v19
	v_add_u32_e32 v20, 19, v20
	v_add_u32_e32 v21, 20, v21
	v_add_u32_e32 v22, 21, v22
	v_add_u32_e32 v23, 22, v23
	v_add_u32_e32 v24, 23, v24
	v_add_u32_e32 v25, 32, v25
	v_add_u32_e32 v26, 33, v26
	v_add_u32_e32 v27, 34, v27
	v_add_u32_e32 v28, 35, v28
	v_add_u32_e32 v29, 36, v29
	v_add_u32_e32 v30, 37, v30
	v_add_u32_e32 v31, 38, v31
	v_add_u32_e32 v32, 39, v32
	v_add_u32_e32 v33, 48, v33
	v_add_u32_e32 v34, 49, v34
	v_add_u32_e32 v35, 50, v35
	v_add_u32_e32 v36, 51, v36
	v_add_u32_e32 v37, 52, v37
	v_add_u32_e32 v38, 53, v38
	v_add_u32_e32 v39, 54, v39
	v_min_u32_e32 v4, 30, v4
	v_add_u32_e32 v11, s36, v11
	s_mulk_i32 s35, 0x7c
	v_cmp_gt_u32_e64 s[40:41], 16, v2
	v_add_u32_e32 v2, 58, v5
	v_min_u32_e32 v7, 30, v7
	v_min_u32_e32 v9, 30, v9
	v_min_u32_e32 v12, 30, v12
	v_min_u32_e32 v13, 30, v13
	v_min_u32_e32 v14, 30, v14
	v_min_u32_e32 v15, 30, v15
	v_min_u32_e32 v16, 30, v16
	v_min_u32_e32 v17, 30, v17
	v_min_u32_e32 v18, 30, v18
	v_min_u32_e32 v19, 30, v19
	v_min_u32_e32 v20, 30, v20
	v_min_u32_e32 v21, 30, v21
	v_min_u32_e32 v22, 30, v22
	v_min_u32_e32 v23, 30, v23
	v_min_u32_e32 v24, 30, v24
	v_min_u32_e32 v25, 30, v25
	v_min_u32_e32 v26, 30, v26
	v_min_u32_e32 v27, 30, v27
	v_min_u32_e32 v28, 30, v28
	v_min_u32_e32 v29, 30, v29
	v_min_u32_e32 v30, 30, v30
	v_min_u32_e32 v31, 30, v31
	v_min_u32_e32 v32, 30, v32
	v_min_u32_e32 v33, 30, v33
	v_min_u32_e32 v34, 30, v34
	v_min_u32_e32 v35, 30, v35
	v_min_u32_e32 v36, 30, v36
	v_min_u32_e32 v37, 30, v37
	v_min_u32_e32 v38, 30, v38
	v_min_u32_e32 v39, 30, v39
	v_lshl_add_u32 v4, v4, 2, v11
	v_lshlrev_b32_e32 v8, 6, v8
	v_cmp_gt_u32_e64 s[38:39], 16, v2
	v_add_u32_e32 v2, 59, v5
	v_lshl_add_u32 v6, v6, 2, v11
	v_lshl_add_u32 v7, v7, 2, v11
	v_lshl_add_u32 v9, v9, 2, v11
	v_lshl_add_u32 v12, v12, 2, v11
	v_lshl_add_u32 v13, v13, 2, v11
	v_lshl_add_u32 v14, v14, 2, v11
	v_lshl_add_u32 v15, v15, 2, v11
	v_lshl_add_u32 v16, v16, 2, v11
	v_lshl_add_u32 v17, v17, 2, v11
	v_lshl_add_u32 v18, v18, 2, v11
	v_lshl_add_u32 v19, v19, 2, v11
	v_lshl_add_u32 v20, v20, 2, v11
	v_lshl_add_u32 v21, v21, 2, v11
	v_lshl_add_u32 v22, v22, 2, v11
	v_lshl_add_u32 v23, v23, 2, v11
	v_lshl_add_u32 v24, v24, 2, v11
	v_lshl_add_u32 v25, v25, 2, v11
	v_lshl_add_u32 v26, v26, 2, v11
	v_lshl_add_u32 v27, v27, 2, v11
	v_lshl_add_u32 v28, v28, 2, v11
	v_lshl_add_u32 v29, v29, 2, v11
	v_lshl_add_u32 v30, v30, 2, v11
	v_lshl_add_u32 v31, v31, 2, v11
	v_lshl_add_u32 v32, v32, 2, v11
	v_lshl_add_u32 v33, v33, 2, v11
	v_lshl_add_u32 v34, v34, 2, v11
	v_lshl_add_u32 v35, v35, 2, v11
	v_lshl_add_u32 v36, v36, 2, v11
	v_lshl_add_u32 v37, v37, 2, v11
	v_lshl_add_u32 v38, v38, 2, v11
	v_lshl_add_u32 v39, v39, 2, v11
	v_subrev_u32_e32 v11, s35, v4
	v_add_u32_e32 v4, 62, v5
	s_lshl_b32 s34, s16, 8
	v_cmp_gt_u32_e64 s[44:45], 16, v2
	v_add_u32_e32 v2, 60, v5
	v_cmp_gt_u32_e64 s[50:51], 16, v4
	v_add_u32_e32 v4, s17, v8
	v_cmp_gt_u32_e64 s[4:5], 16, v2
	v_add_u32_e32 v2, 61, v5
	s_or_b32 s6, s34, s6
	v_add_u32_e32 v4, v10, v4
	s_lshl_b32 s7, s16, 9
	v_cmp_gt_u32_e64 s[42:43], 16, v2
	v_add_u32_e32 v2, s6, v10
	v_add_u32_e32 v4, 0xffffff00, v4
	v_readlane_b32 s6, v254, 49
	v_add_u32_e32 v40, 63, v5
	v_ashrrev_i32_e32 v5, 31, v4
	s_add_u32 s6, s6, s7
	v_readlane_b32 s7, v254, 50
	v_mov_b32_e32 v1, v201
	v_subrev_u32_e32 v32, s35, v32
	v_subrev_u32_e32 v33, s35, v33
	v_subrev_u32_e32 v34, s35, v34
	v_subrev_u32_e32 v35, s35, v35
	v_subrev_u32_e32 v36, s35, v36
	v_subrev_u32_e32 v37, s35, v37
	v_subrev_u32_e32 v38, s35, v38
	v_subrev_u32_e32 v39, s35, v39
	v_lshlrev_b64 v[4:5], 12, v[4:5]
	s_addc_u32 s7, s7, 0
	s_waitcnt vmcnt(29)
	v_mul_u32_u24_e32 v154, 0x90, v3
	v_ashrrev_i32_e32 v3, 31, v2
	v_mov_b32_e32 v46, v201
	v_mov_b32_e32 v47, v201
	v_subrev_u32_e32 v6, s35, v6
	v_subrev_u32_e32 v7, s35, v7
	v_subrev_u32_e32 v9, s35, v9
	v_subrev_u32_e32 v12, s35, v12
	v_subrev_u32_e32 v13, s35, v13
	v_subrev_u32_e32 v14, s35, v14
	v_subrev_u32_e32 v15, s35, v15
	v_subrev_u32_e32 v16, s35, v16
	v_subrev_u32_e32 v17, s35, v17
	v_subrev_u32_e32 v18, s35, v18
	v_subrev_u32_e32 v19, s35, v19
	v_subrev_u32_e32 v20, s35, v20
	v_subrev_u32_e32 v21, s35, v21
	v_subrev_u32_e32 v22, s35, v22
	v_subrev_u32_e32 v23, s35, v23
	v_subrev_u32_e32 v24, s35, v24
	v_subrev_u32_e32 v25, s35, v25
	v_subrev_u32_e32 v26, s35, v26
	v_subrev_u32_e32 v27, s35, v27
	v_subrev_u32_e32 v28, s35, v28
	v_subrev_u32_e32 v29, s35, v29
	v_subrev_u32_e32 v30, s35, v30
	v_subrev_u32_e32 v31, s35, v31
	v_lshl_add_u64 v[150:151], s[6:7], 0, v[4:5]
	v_cmp_gt_u32_e64 s[6:7], 16, v40
	v_add_u32_e32 v178, s23, v32
	v_add_u32_e32 v179, s23, v33
	v_add_u32_e32 v180, s23, v34
	v_add_u32_e32 v181, s23, v35
	v_add_u32_e32 v182, s23, v36
	v_add_u32_e32 v183, s23, v37
	v_add_u32_e32 v184, s23, v38
	v_add_u32_e32 v185, s23, v39
	v_lshlrev_b64 v[2:3], 14, v[2:3]
	v_lshl_add_u64 v[0:1], s[10:11], 0, v[0:1]
	v_mov_b32_e32 v32, v201
	v_mov_b32_e32 v33, v201
	v_mov_b32_e32 v34, v201
	v_mov_b32_e32 v35, v201
	v_mov_b32_e32 v36, v201
	v_mov_b32_e32 v37, v201
	v_mov_b32_e32 v38, v201
	v_mov_b32_e32 v39, v201
	v_mov_b32_e32 v40, v201
	v_mov_b32_e32 v41, v201
	v_mov_b32_e32 v42, v201
	v_mov_b32_e32 v43, v201
	v_mov_b32_e32 v44, v201
	v_mov_b32_e32 v45, v201
	v_mov_b32_e32 v187, 0
	v_mov_b64_e32 v[62:63], v[46:47]
	s_mov_b32 s16, 0
	v_add_u32_e32 v155, s23, v6
	s_waitcnt vmcnt(28)
	v_add_u32_e32 v156, s23, v7
	v_add_u32_e32 v157, s23, v9
	v_add_u32_e32 v158, s23, v12
	v_add_u32_e32 v159, s23, v13
	v_add_u32_e32 v160, s23, v14
	v_add_u32_e32 v161, s23, v15
	v_add_u32_e32 v162, s23, v16
	v_add_u32_e32 v163, s23, v17
	v_add_u32_e32 v164, s23, v18
	v_add_u32_e32 v165, s23, v19
	v_add_u32_e32 v166, s23, v20
	v_add_u32_e32 v167, s23, v21
	v_add_u32_e32 v168, s23, v22
	v_add_u32_e32 v169, s23, v23
	v_add_u32_e32 v170, s23, v24
	v_add_u32_e32 v171, s23, v25
	v_add_u32_e32 v172, s23, v26
	v_add_u32_e32 v173, s23, v27
	v_add_u32_e32 v174, s23, v28
	v_add_u32_e32 v175, s23, v29
	v_add_u32_e32 v176, s23, v30
	v_add_u32_e32 v177, s23, v31
	v_add_u32_e32 v186, s23, v11
	v_lshl_add_u64 v[152:153], v[0:1], 0, v[2:3]
	v_mov_b64_e32 v[60:61], v[44:45]
	v_mov_b64_e32 v[58:59], v[42:43]
	v_mov_b64_e32 v[56:57], v[40:41]
	v_mov_b64_e32 v[54:55], v[38:39]
	v_mov_b64_e32 v[52:53], v[36:37]
	v_mov_b64_e32 v[50:51], v[34:35]
	v_mov_b64_e32 v[48:49], v[32:33]
	v_mov_b32_e32 v188, 0
	v_mov_b32_e32 v64, 0
	v_mov_b32_e32 v65, v187
	v_mov_b32_e32 v66, v187
	v_mov_b32_e32 v67, v187
	v_mov_b32_e32 v68, v187
	v_mov_b32_e32 v69, v187
	v_mov_b32_e32 v70, v187
	v_mov_b32_e32 v71, v187
	v_mov_b32_e32 v72, v187
	v_mov_b32_e32 v73, v187
	v_mov_b32_e32 v74, v187
	v_mov_b32_e32 v75, v187
	v_mov_b32_e32 v76, v187
	v_mov_b32_e32 v77, v187
	v_mov_b32_e32 v78, v187
	v_mov_b32_e32 v79, v187
	s_mov_b32 s36, 0
	s_add_i32 s99, s99, 1
	s_and_b32 s99, s99, 7
	s_lshl_b32 s13, s99, 18
	v_add_co_u32_e32 v150, vcc, s13, v150
	v_addc_co_u32_e32 v151, vcc, 0, v151, vcc
	v_add_co_u32_e32 v150, vcc, 0xfffc0000, v150
	v_addc_co_u32_e32 v151, vcc, -1, v151, vcc
	s_lshl_b32 s13, s99, 7
	v_add_co_u32_e32 v152, vcc, s13, v152
	v_addc_co_u32_e32 v153, vcc, 0, v153, vcc
	v_add_co_u32_e32 v152, vcc, 0xffffff80, v152
	v_addc_co_u32_e32 v153, vcc, -1, v153, vcc
	s_waitcnt vmcnt(7)
	ds_write_b128 v147, v[112:115] offset:9216
	s_waitcnt vmcnt(6)
	ds_write_b128 v147, v[116:119] offset:27648
	s_waitcnt vmcnt(5)
	ds_write_b128 v147, v[132:135] offset:46080
	s_waitcnt vmcnt(4)
	ds_write_b128 v147, v[140:143] offset:64512
	s_waitcnt vmcnt(3)
	ds_write_b128 v147, v[120:123]
	s_waitcnt vmcnt(2)
	ds_write_b128 v147, v[124:127] offset:18432
	s_waitcnt vmcnt(1)
	ds_write_b128 v147, v[128:131] offset:36864
	s_waitcnt vmcnt(0)
	ds_write_b128 v147, v[136:139] offset:55296
	s_waitcnt lgkmcnt(0)
	s_barrier
	s_branch .LBB0_284
